# GEMM unit headers: accumulator zero-init with v_mov_b64 (63 moves) instead of 126 v_mov_b32
# speedup vs baseline: 1.0104x; 1.0010x over previous
.LBB0_174:
	s_xor_b64 s[10:11], s[8:9], -1
	s_mov_b32 s24, s29
	v_writelane_b32 v252, s10, 49
	s_ashr_i32 s25, s29, 31
	s_nop 0
	v_writelane_b32 v252, s11, 50
	s_lshl_b64 s[10:11], s[24:25], 19
	v_readlane_b32 s62, v253, 40
	v_readlane_b32 s63, v253, 41
	s_add_u32 s20, s62, s10
	s_addc_u32 s21, s63, s11
	s_and_b64 s[10:11], s[8:9], exec
	s_mov_b32 s16, s30
	s_cselect_b32 s10, s21, s5
	s_cselect_b32 s11, s20, s4
	s_ashr_i32 s17, s30, 31
	v_readlane_b32 s64, v253, 42
	s_lshl_b64 s[30:31], s[16:17], 19
	v_readlane_b32 s65, v253, 43
	s_add_u32 s54, s64, s30
	s_addc_u32 s55, s65, s31
	s_and_b64 s[8:9], s[8:9], exec
	s_cselect_b32 s25, s55, s7
	s_cselect_b32 s29, s54, s6
	s_add_u32 s4, s4, 0x40080
	s_addc_u32 s5, s5, 0
	s_add_u32 s30, s6, 0x100
	v_mov_b32_e32 v0, 0
	s_addc_u32 s31, s7, 0
	s_mov_b32 s34, -2
	v_mov_b32_e32 v1, v0
	v_mov_b64_e32 v[2:3], 0
	v_mov_b64_e32 v[4:5], 0
	v_mov_b64_e32 v[6:7], 0
	v_mov_b64_e32 v[32:33], 0
	v_mov_b64_e32 v[34:35], 0
	v_mov_b64_e32 v[36:37], 0
	v_mov_b64_e32 v[38:39], 0
	v_mov_b64_e32 v[64:65], 0
	v_mov_b64_e32 v[66:67], 0
	v_mov_b64_e32 v[68:69], 0
	v_mov_b64_e32 v[70:71], 0
	v_mov_b64_e32 v[80:81], 0
	s_waitcnt lgkmcnt(0)
	v_mov_b64_e32 v[82:83], 0
	v_mov_b64_e32 v[84:85], 0
	v_mov_b64_e32 v[86:87], 0
	v_mov_b64_e32 v[8:9], 0
	v_mov_b64_e32 v[10:11], 0
	v_mov_b64_e32 v[12:13], 0
	v_mov_b64_e32 v[14:15], 0
	v_mov_b64_e32 v[56:57], 0
	v_mov_b64_e32 v[58:59], 0
	v_mov_b64_e32 v[60:61], 0
	v_mov_b64_e32 v[62:63], 0
	v_mov_b64_e32 v[72:73], 0
	v_mov_b64_e32 v[74:75], 0
	v_mov_b64_e32 v[76:77], 0
	v_mov_b64_e32 v[78:79], 0
	v_mov_b64_e32 v[88:89], 0
	v_mov_b64_e32 v[90:91], 0
	v_mov_b64_e32 v[92:93], 0
	v_mov_b64_e32 v[94:95], 0
	v_mov_b64_e32 v[96:97], 0
	v_mov_b64_e32 v[98:99], 0
	v_mov_b64_e32 v[100:101], 0
	v_mov_b64_e32 v[102:103], 0
	v_mov_b64_e32 v[112:113], 0
	v_mov_b64_e32 v[114:115], 0
	v_mov_b64_e32 v[116:117], 0
	v_mov_b64_e32 v[118:119], 0
	v_mov_b64_e32 v[128:129], 0
	v_mov_b64_e32 v[130:131], 0
	v_mov_b64_e32 v[132:133], 0
	v_mov_b64_e32 v[134:135], 0
	v_mov_b64_e32 v[144:145], 0
	v_mov_b64_e32 v[146:147], 0
	v_mov_b64_e32 v[148:149], 0
	v_mov_b64_e32 v[150:151], 0
	v_mov_b64_e32 v[104:105], 0
	v_mov_b64_e32 v[106:107], 0
	v_mov_b64_e32 v[108:109], 0
	v_mov_b64_e32 v[110:111], 0
	v_mov_b64_e32 v[120:121], 0
	v_mov_b64_e32 v[122:123], 0
	v_mov_b64_e32 v[124:125], 0
	v_mov_b64_e32 v[126:127], 0
	v_mov_b64_e32 v[136:137], 0
	v_mov_b64_e32 v[138:139], 0
	v_mov_b64_e32 v[140:141], 0
	v_mov_b64_e32 v[142:143], 0
	v_mov_b64_e32 v[152:153], 0
	v_mov_b64_e32 v[154:155], 0
	v_mov_b64_e32 v[156:157], 0
	v_mov_b64_e32 v[158:159], 0
	s_nop 2
	v_readlane_b32 s60, v253, 38
	v_readlane_b32 s61, v253, 39
	s_nop 5
	s_waitcnt vmcnt(0)

.LBB0_611:
	s_ashr_i32 s9, s8, 31
	s_xor_b64 s[10:11], s[34:35], -1
	s_lshl_b64 s[14:15], s[8:9], 19
	v_readlane_b32 s44, v252, 7
	v_readlane_b32 s45, v252, 8
	s_add_u32 s7, s44, s14
	s_addc_u32 s9, s45, s15
	s_lshl_b32 s42, s40, 7
	s_add_u32 s14, s7, s42
	s_addc_u32 s15, s9, 0
	s_and_b64 s[16:17], s[34:35], exec
	s_cselect_b32 s9, s15, s23
	s_cselect_b32 s41, s14, s22
	s_ashr_i32 s7, s6, 31
	s_lshl_b64 s[16:17], s[6:7], 20
	s_add_u32 s7, s68, s16
	s_addc_u32 s17, s69, s17
	s_add_u32 s16, s7, s42
	s_addc_u32 s17, s17, 0
	s_and_b64 s[34:35], s[34:35], exec
	s_cselect_b32 s7, s17, s25
	s_cselect_b32 s42, s16, s24
	s_add_u32 s22, s22, 0x40080
	s_addc_u32 s23, s23, 0
	s_add_u32 s43, s24, 0x100
	v_mov_b32_e32 v0, 0
	s_addc_u32 s44, s25, 0
	s_mov_b32 s45, -2
	v_mov_b32_e32 v1, v0
	v_mov_b64_e32 v[2:3], 0
	v_mov_b64_e32 v[4:5], 0
	v_mov_b64_e32 v[6:7], 0
	v_mov_b64_e32 v[8:9], 0
	v_mov_b64_e32 v[10:11], 0
	v_mov_b64_e32 v[12:13], 0
	v_mov_b64_e32 v[14:15], 0
	v_mov_b64_e32 v[16:17], 0
	v_mov_b64_e32 v[18:19], 0
	v_mov_b64_e32 v[20:21], 0
	v_mov_b64_e32 v[22:23], 0
	v_mov_b64_e32 v[32:33], 0
	v_mov_b64_e32 v[34:35], 0
	v_mov_b64_e32 v[36:37], 0
	v_mov_b64_e32 v[38:39], 0
	v_mov_b64_e32 v[24:25], 0
	v_mov_b64_e32 v[26:27], 0
	v_mov_b64_e32 v[28:29], 0
	v_mov_b64_e32 v[30:31], 0
	v_mov_b64_e32 v[40:41], 0
	v_mov_b64_e32 v[42:43], 0
	v_mov_b64_e32 v[44:45], 0
	v_mov_b64_e32 v[46:47], 0
	v_mov_b64_e32 v[48:49], 0
	v_mov_b64_e32 v[50:51], 0
	v_mov_b64_e32 v[52:53], 0
	v_mov_b64_e32 v[54:55], 0
	v_mov_b64_e32 v[56:57], 0
	v_mov_b64_e32 v[58:59], 0
	v_mov_b64_e32 v[60:61], 0
	v_mov_b64_e32 v[62:63], 0
	v_mov_b64_e32 v[64:65], 0
	v_mov_b64_e32 v[66:67], 0
	v_mov_b64_e32 v[68:69], 0
	v_mov_b64_e32 v[70:71], 0
	v_mov_b64_e32 v[72:73], 0
	v_mov_b64_e32 v[74:75], 0
	v_mov_b64_e32 v[76:77], 0
	v_mov_b64_e32 v[78:79], 0
	v_mov_b64_e32 v[80:81], 0
	v_mov_b64_e32 v[82:83], 0
	v_mov_b64_e32 v[88:89], 0
	v_mov_b64_e32 v[90:91], 0
	v_mov_b64_e32 v[96:97], 0
	v_mov_b64_e32 v[98:99], 0
	v_mov_b64_e32 v[104:105], 0
	v_mov_b64_e32 v[106:107], 0
	v_mov_b64_e32 v[84:85], 0
	v_mov_b64_e32 v[86:87], 0
	v_mov_b64_e32 v[92:93], 0
	v_mov_b64_e32 v[94:95], 0
	v_mov_b64_e32 v[100:101], 0
	v_mov_b64_e32 v[102:103], 0
	v_mov_b64_e32 v[108:109], 0
	v_mov_b64_e32 v[110:111], 0
	v_mov_b64_e32 v[112:113], 0
	v_mov_b64_e32 v[114:115], 0
	v_mov_b64_e32 v[116:117], 0
	v_mov_b64_e32 v[118:119], 0
	v_mov_b64_e32 v[120:121], 0
	v_mov_b64_e32 v[122:123], 0
	v_mov_b64_e32 v[124:125], 0
	v_mov_b64_e32 v[126:127], 0
	s_nop 7
	s_nop 5

.LBB0_1267:
	s_ashr_i32 s13, s12, 31
	s_xor_b64 s[18:19], s[24:25], -1
	s_lshl_b64 s[16:17], s[12:13], 18
	s_add_u32 s16, s80, s16
	s_addc_u32 s17, s81, s17
	s_and_b64 s[20:21], s[24:25], exec
	s_nop 0
	s_cselect_b32 s13, s17, s11
	s_cselect_b32 s40, s16, s10
	s_ashr_i32 s15, s14, 31
	s_nop 1
	v_readlane_b32 s54, v253, 44
	v_readlane_b32 s55, v253, 45
	s_lshl_b64 s[20:21], s[14:15], 18
	s_mov_b64 s[50:51], s[54:55]
	s_add_u32 s20, s50, s20
	s_addc_u32 s21, s51, s21
	s_and_b64 s[24:25], s[24:25], exec
	s_cselect_b32 s15, s21, s23
	s_cselect_b32 s41, s20, s22
	s_add_u32 s10, s10, 0x20080
	s_addc_u32 s11, s11, 0
	s_add_u32 s42, s22, 0x100
	v_mov_b32_e32 v0, 0
	s_addc_u32 s43, s23, 0
	s_mov_b32 s44, -2
	v_mov_b32_e32 v1, v0
	v_mov_b64_e32 v[2:3], 0
	v_mov_b64_e32 v[4:5], 0
	v_mov_b64_e32 v[6:7], 0
	v_mov_b64_e32 v[12:13], 0
	v_mov_b64_e32 v[14:15], 0
	v_mov_b64_e32 v[20:21], 0
	v_mov_b64_e32 v[22:23], 0
	v_mov_b64_e32 v[28:29], 0
	v_mov_b64_e32 v[30:31], 0
	v_mov_b64_e32 v[36:37], 0
	v_mov_b64_e32 v[38:39], 0
	v_mov_b64_e32 v[44:45], 0
	v_mov_b64_e32 v[46:47], 0
	v_mov_b64_e32 v[52:53], 0
	v_mov_b64_e32 v[54:55], 0
	v_mov_b64_e32 v[8:9], 0
	v_mov_b64_e32 v[10:11], 0
	v_mov_b64_e32 v[16:17], 0
	v_mov_b64_e32 v[18:19], 0
	v_mov_b64_e32 v[24:25], 0
	v_mov_b64_e32 v[26:27], 0
	v_mov_b64_e32 v[32:33], 0
	v_mov_b64_e32 v[34:35], 0
	v_mov_b64_e32 v[40:41], 0
	v_mov_b64_e32 v[42:43], 0
	v_mov_b64_e32 v[48:49], 0
	v_mov_b64_e32 v[50:51], 0
	v_mov_b64_e32 v[56:57], 0
	v_mov_b64_e32 v[58:59], 0
	v_mov_b64_e32 v[60:61], 0
	v_mov_b64_e32 v[62:63], 0
	v_mov_b64_e32 v[64:65], 0
	v_mov_b64_e32 v[66:67], 0
	v_mov_b64_e32 v[68:69], 0
	v_mov_b64_e32 v[70:71], 0
	v_mov_b64_e32 v[76:77], 0
	v_mov_b64_e32 v[78:79], 0
	v_mov_b64_e32 v[84:85], 0
	v_mov_b64_e32 v[86:87], 0
	v_mov_b64_e32 v[92:93], 0
	v_mov_b64_e32 v[94:95], 0
	v_mov_b64_e32 v[100:101], 0
	v_mov_b64_e32 v[102:103], 0
	v_mov_b64_e32 v[108:109], 0
	v_mov_b64_e32 v[110:111], 0
	v_mov_b64_e32 v[116:117], 0
	v_mov_b64_e32 v[118:119], 0
	v_mov_b64_e32 v[72:73], 0
	v_mov_b64_e32 v[74:75], 0
	v_mov_b64_e32 v[80:81], 0
	v_mov_b64_e32 v[82:83], 0
	v_mov_b64_e32 v[88:89], 0
	v_mov_b64_e32 v[90:91], 0
	v_mov_b64_e32 v[96:97], 0
	v_mov_b64_e32 v[98:99], 0
	v_mov_b64_e32 v[104:105], 0
	v_mov_b64_e32 v[106:107], 0
	v_mov_b64_e32 v[112:113], 0
	v_mov_b64_e32 v[114:115], 0
	v_mov_b64_e32 v[120:121], 0
	v_mov_b64_e32 v[122:123], 0
	v_mov_b64_e32 v[124:125], 0
	v_mov_b64_e32 v[126:127], 0
	s_nop 7
	s_nop 2

.LBB0_1284:
	s_nop 0
	s_ashr_i32 s13, s12, 31
	s_nop 1
	v_readlane_b32 s54, v252, 21
	v_readlane_b32 s55, v252, 22
	s_xor_b64 s[18:19], s[24:25], -1
	s_lshl_b64 s[16:17], s[12:13], 18
	s_mov_b64 s[50:51], s[54:55]
	s_add_u32 s16, s50, s16
	s_addc_u32 s17, s51, s17
	s_nop 7
	s_nop 2
	s_and_b64 s[20:21], s[24:25], exec
	s_cselect_b32 s13, s17, s11
	s_cselect_b32 s39, s16, s10
	s_ashr_i32 s15, s14, 31
	s_nop 0
	s_lshl_b64 s[20:21], s[14:15], 18
	v_readlane_b32 s52, v253, 46
	v_readlane_b32 s53, v253, 47
	s_add_u32 s20, s52, s20
	s_addc_u32 s21, s53, s21
	s_and_b64 s[24:25], s[24:25], exec
	s_cselect_b32 s15, s21, s23
	s_cselect_b32 s40, s20, s22
	s_add_u32 s10, s10, 0x20080
	s_nop 0
	s_addc_u32 s11, s11, 0
	s_nop 1
	s_add_u32 s41, s22, 0x100
	v_mov_b32_e32 v0, 0
	s_addc_u32 s42, s23, 0
	s_mov_b32 s43, -2
	v_mov_b32_e32 v1, v0
	v_mov_b64_e32 v[2:3], 0
	v_mov_b64_e32 v[4:5], 0
	v_mov_b64_e32 v[6:7], 0
	v_mov_b64_e32 v[16:17], 0
	v_mov_b64_e32 v[18:19], 0
	v_mov_b64_e32 v[20:21], 0
	v_mov_b64_e32 v[22:23], 0
	v_mov_b64_e32 v[32:33], 0
	v_mov_b64_e32 v[34:35], 0
	v_mov_b64_e32 v[36:37], 0
	v_mov_b64_e32 v[38:39], 0
	v_mov_b64_e32 v[48:49], 0
	v_mov_b64_e32 v[50:51], 0
	v_mov_b64_e32 v[52:53], 0
	v_mov_b64_e32 v[54:55], 0
	v_mov_b64_e32 v[8:9], 0
	v_mov_b64_e32 v[10:11], 0
	v_mov_b64_e32 v[12:13], 0
	v_mov_b64_e32 v[14:15], 0
	v_mov_b64_e32 v[24:25], 0
	v_mov_b64_e32 v[26:27], 0
	v_mov_b64_e32 v[28:29], 0
	v_mov_b64_e32 v[30:31], 0
	v_mov_b64_e32 v[40:41], 0
	v_mov_b64_e32 v[42:43], 0
	v_mov_b64_e32 v[44:45], 0
	v_mov_b64_e32 v[46:47], 0
	v_mov_b64_e32 v[56:57], 0
	v_mov_b64_e32 v[58:59], 0
	v_mov_b64_e32 v[60:61], 0
	v_mov_b64_e32 v[62:63], 0
	v_mov_b64_e32 v[64:65], 0
	v_mov_b64_e32 v[66:67], 0
	v_mov_b64_e32 v[68:69], 0
	v_mov_b64_e32 v[70:71], 0
	v_mov_b64_e32 v[80:81], 0
	v_mov_b64_e32 v[82:83], 0
	v_mov_b64_e32 v[84:85], 0
	v_mov_b64_e32 v[86:87], 0
	v_mov_b64_e32 v[96:97], 0
	v_mov_b64_e32 v[98:99], 0
	v_mov_b64_e32 v[100:101], 0
	v_mov_b64_e32 v[102:103], 0
	v_mov_b64_e32 v[112:113], 0
	v_mov_b64_e32 v[114:115], 0
	v_mov_b64_e32 v[116:117], 0
	v_mov_b64_e32 v[118:119], 0
	v_mov_b64_e32 v[72:73], 0
	v_mov_b64_e32 v[74:75], 0
	v_mov_b64_e32 v[76:77], 0
	v_mov_b64_e32 v[78:79], 0
	v_mov_b64_e32 v[88:89], 0
	v_mov_b64_e32 v[90:91], 0
	v_mov_b64_e32 v[92:93], 0
	v_mov_b64_e32 v[94:95], 0
	v_mov_b64_e32 v[104:105], 0
	v_mov_b64_e32 v[106:107], 0
	v_mov_b64_e32 v[108:109], 0
	v_mov_b64_e32 v[110:111], 0
	v_mov_b64_e32 v[120:121], 0
	v_mov_b64_e32 v[122:123], 0
	v_mov_b64_e32 v[124:125], 0
	v_mov_b64_e32 v[126:127], 0
	s_nop 7
	s_nop 1

.LBB0_1355:
	s_mov_b32 s14, s17
	s_ashr_i32 s15, s17, 31
	s_mov_b32 s16, s20
	s_xor_b64 s[20:21], s[26:27], -1
	s_lshl_b64 s[18:19], s[14:15], 19
	s_add_u32 s18, s82, s18
	s_addc_u32 s19, s83, s19
	s_and_b64 s[22:23], s[26:27], exec
	s_cselect_b32 s15, s19, s11
	s_cselect_b32 s29, s18, s10
	s_ashr_i32 s17, s16, 31
	s_nop 0
	s_lshl_b64 s[22:23], s[16:17], 19
	v_readlane_b32 s58, v253, 48
	v_readlane_b32 s59, v253, 49
	s_add_u32 s22, s58, s22
	s_addc_u32 s23, s59, s23
	s_and_b64 s[26:27], s[26:27], exec
	s_cselect_b32 s17, s23, s25
	s_cselect_b32 s44, s22, s24
	s_add_u32 s10, s10, 0x40080
	s_nop 0
	s_addc_u32 s11, s11, 0
	s_nop 1
	s_add_u32 s45, s24, 0x100
	v_mov_b32_e32 v0, 0
	s_addc_u32 s46, s25, 0
	s_mov_b32 s47, -2
	s_waitcnt lgkmcnt(0)
	v_mov_b32_e32 v1, v0
	v_mov_b64_e32 v[2:3], 0
	v_mov_b64_e32 v[4:5], 0
	v_mov_b64_e32 v[6:7], 0
	v_mov_b64_e32 v[16:17], 0
	v_mov_b64_e32 v[18:19], 0
	v_mov_b64_e32 v[20:21], 0
	v_mov_b64_e32 v[22:23], 0
	v_mov_b64_e32 v[32:33], 0
	v_mov_b64_e32 v[34:35], 0
	v_mov_b64_e32 v[36:37], 0
	v_mov_b64_e32 v[38:39], 0
	v_mov_b64_e32 v[48:49], 0
	v_mov_b64_e32 v[50:51], 0
	v_mov_b64_e32 v[52:53], 0
	v_mov_b64_e32 v[54:55], 0
	v_mov_b64_e32 v[8:9], 0
	v_mov_b64_e32 v[10:11], 0
	v_mov_b64_e32 v[12:13], 0
	v_mov_b64_e32 v[14:15], 0
	v_mov_b64_e32 v[24:25], 0
	v_mov_b64_e32 v[26:27], 0
	v_mov_b64_e32 v[28:29], 0
	v_mov_b64_e32 v[30:31], 0
	v_mov_b64_e32 v[40:41], 0
	v_mov_b64_e32 v[42:43], 0
	v_mov_b64_e32 v[44:45], 0
	v_mov_b64_e32 v[46:47], 0
	v_mov_b64_e32 v[56:57], 0
	v_mov_b64_e32 v[58:59], 0
	v_mov_b64_e32 v[60:61], 0
	v_mov_b64_e32 v[62:63], 0
	v_mov_b64_e32 v[64:65], 0
	v_mov_b64_e32 v[66:67], 0
	v_mov_b64_e32 v[68:69], 0
	v_mov_b64_e32 v[70:71], 0
	v_mov_b64_e32 v[80:81], 0
	v_mov_b64_e32 v[82:83], 0
	v_mov_b64_e32 v[84:85], 0
	v_mov_b64_e32 v[86:87], 0
	v_mov_b64_e32 v[96:97], 0
	v_mov_b64_e32 v[98:99], 0
	v_mov_b64_e32 v[100:101], 0
	v_mov_b64_e32 v[102:103], 0
	v_mov_b64_e32 v[112:113], 0
	v_mov_b64_e32 v[114:115], 0
	v_mov_b64_e32 v[116:117], 0
	v_mov_b64_e32 v[118:119], 0
	v_mov_b64_e32 v[72:73], 0
	v_mov_b64_e32 v[74:75], 0
	v_mov_b64_e32 v[76:77], 0
	v_mov_b64_e32 v[78:79], 0
	v_mov_b64_e32 v[88:89], 0
	v_mov_b64_e32 v[90:91], 0
	v_mov_b64_e32 v[92:93], 0
	v_mov_b64_e32 v[94:95], 0
	v_mov_b64_e32 v[104:105], 0
	v_mov_b64_e32 v[106:107], 0
	v_mov_b64_e32 v[108:109], 0
	v_mov_b64_e32 v[110:111], 0
	v_mov_b64_e32 v[120:121], 0
	v_mov_b64_e32 v[122:123], 0
	v_mov_b64_e32 v[124:125], 0
	v_mov_b64_e32 v[126:127], 0
	s_nop 7
	s_nop 1

.LBB0_1440:
	s_nop 3
	v_readlane_b32 s48, v253, 38
	v_readlane_b32 s49, v253, 39
	s_ashr_i32 s19, s18, 31
	v_readlane_b32 s50, v253, 40
	v_readlane_b32 s51, v253, 41
	s_mov_b64 s[44:45], s[48:49]
	s_xor_b64 s[24:25], s[10:11], -1
	s_lshl_b64 s[22:23], s[18:19], 19
	s_mov_b64 s[46:47], s[50:51]
	s_add_u32 s22, s46, s22
	s_addc_u32 s23, s47, s23
	s_and_b64 s[26:27], s[10:11], exec
	s_cselect_b32 s19, s23, s1
	s_cselect_b32 s41, s22, s0
	s_ashr_i32 s21, s20, 31
	s_lshl_b64 s[26:27], s[20:21], 19
	s_add_u32 s26, s64, s26
	s_addc_u32 s27, s65, s27
	s_and_b64 s[10:11], s[10:11], exec
	s_cselect_b32 s21, s27, s5
	s_cselect_b32 s42, s26, s4
	s_add_u32 s0, s0, 0x40080
	s_addc_u32 s1, s1, 0
	s_add_u32 s43, s4, 0x100
	v_mov_b32_e32 v0, 0
	s_addc_u32 s44, s5, 0
	s_mov_b32 s45, -2
	v_mov_b32_e32 v1, v0
	v_mov_b64_e32 v[2:3], 0
	v_mov_b64_e32 v[4:5], 0
	v_mov_b64_e32 v[6:7], 0
	v_mov_b64_e32 v[16:17], 0
	v_mov_b64_e32 v[18:19], 0
	v_mov_b64_e32 v[20:21], 0
	v_mov_b64_e32 v[22:23], 0
	v_mov_b64_e32 v[32:33], 0
	v_mov_b64_e32 v[34:35], 0
	v_mov_b64_e32 v[36:37], 0
	v_mov_b64_e32 v[38:39], 0
	v_mov_b64_e32 v[48:49], 0
	v_mov_b64_e32 v[50:51], 0
	v_mov_b64_e32 v[52:53], 0
	v_mov_b64_e32 v[54:55], 0
	v_mov_b64_e32 v[8:9], 0
	v_mov_b64_e32 v[10:11], 0
	v_mov_b64_e32 v[12:13], 0
	v_mov_b64_e32 v[14:15], 0
	v_mov_b64_e32 v[24:25], 0
	v_mov_b64_e32 v[26:27], 0
	v_mov_b64_e32 v[28:29], 0
	v_mov_b64_e32 v[30:31], 0
	v_mov_b64_e32 v[40:41], 0
	v_mov_b64_e32 v[42:43], 0
	v_mov_b64_e32 v[44:45], 0
	v_mov_b64_e32 v[46:47], 0
	v_mov_b64_e32 v[56:57], 0
	v_mov_b64_e32 v[58:59], 0
	v_mov_b64_e32 v[60:61], 0
	v_mov_b64_e32 v[62:63], 0
	v_mov_b64_e32 v[64:65], 0
	v_mov_b64_e32 v[66:67], 0
	v_mov_b64_e32 v[68:69], 0
	v_mov_b64_e32 v[70:71], 0
	v_mov_b64_e32 v[80:81], 0
	v_mov_b64_e32 v[82:83], 0
	v_mov_b64_e32 v[84:85], 0
	v_mov_b64_e32 v[86:87], 0
	v_mov_b64_e32 v[96:97], 0
	v_mov_b64_e32 v[98:99], 0
	v_mov_b64_e32 v[100:101], 0
	v_mov_b64_e32 v[102:103], 0
	v_mov_b64_e32 v[112:113], 0
	v_mov_b64_e32 v[114:115], 0
	v_mov_b64_e32 v[116:117], 0
	v_mov_b64_e32 v[118:119], 0
	v_mov_b64_e32 v[72:73], 0
	v_mov_b64_e32 v[74:75], 0
	v_mov_b64_e32 v[76:77], 0
	v_mov_b64_e32 v[78:79], 0
	v_mov_b64_e32 v[88:89], 0
	v_mov_b64_e32 v[90:91], 0
	v_mov_b64_e32 v[92:93], 0
	v_mov_b64_e32 v[94:95], 0
	v_mov_b64_e32 v[104:105], 0
	v_mov_b64_e32 v[106:107], 0
	v_mov_b64_e32 v[108:109], 0
	v_mov_b64_e32 v[110:111], 0
	v_mov_b64_e32 v[120:121], 0
	v_mov_b64_e32 v[122:123], 0
	v_mov_b64_e32 v[124:125], 0
	v_mov_b64_e32 v[126:127], 0
	s_nop 7

.LBB0_1511:
	s_ashr_i32 s15, s14, 31
	s_xor_b64 s[20:21], s[28:29], -1
	s_lshl_b64 s[18:19], s[14:15], 15
	s_add_u32 s18, s84, s18
	s_addc_u32 s19, s85, s19
	s_and_b64 s[22:23], s[28:29], exec
	s_cselect_b32 s5, s19, s27
	s_cselect_b32 s7, s18, s26
	s_ashr_i32 s17, s16, 31
	s_lshl_b64 s[22:23], s[16:17], 15
	s_add_u32 s22, s66, s22
	s_addc_u32 s23, s67, s23
	s_and_b64 s[28:29], s[28:29], exec
	s_cselect_b32 s8, s23, s25
	s_cselect_b32 s15, s22, s24
	s_add_u32 s17, s24, 0x40000
	s_addc_u32 s48, s25, 0
	s_add_u32 s24, s26, 0x404000
	v_mov_b32_e32 v0, 0
	s_addc_u32 s25, s27, 0
	s_mov_b32 s49, -2
	v_mov_b32_e32 v1, v0
	v_mov_b64_e32 v[2:3], 0
	v_mov_b64_e32 v[4:5], 0
	v_mov_b64_e32 v[6:7], 0
	v_mov_b64_e32 v[16:17], 0
	v_mov_b64_e32 v[18:19], 0
	v_mov_b64_e32 v[20:21], 0
	v_mov_b64_e32 v[22:23], 0
	v_mov_b64_e32 v[32:33], 0
	v_mov_b64_e32 v[34:35], 0
	v_mov_b64_e32 v[36:37], 0
	v_mov_b64_e32 v[38:39], 0
	v_mov_b64_e32 v[48:49], 0
	v_mov_b64_e32 v[50:51], 0
	v_mov_b64_e32 v[52:53], 0
	v_mov_b64_e32 v[54:55], 0
	v_mov_b64_e32 v[8:9], 0
	v_mov_b64_e32 v[10:11], 0
	v_mov_b64_e32 v[12:13], 0
	v_mov_b64_e32 v[14:15], 0
	v_mov_b64_e32 v[24:25], 0
	v_mov_b64_e32 v[26:27], 0
	v_mov_b64_e32 v[28:29], 0
	v_mov_b64_e32 v[30:31], 0
	v_mov_b64_e32 v[40:41], 0
	v_mov_b64_e32 v[42:43], 0
	v_mov_b64_e32 v[44:45], 0
	v_mov_b64_e32 v[46:47], 0
	v_mov_b64_e32 v[56:57], 0
	v_mov_b64_e32 v[58:59], 0
	v_mov_b64_e32 v[60:61], 0
	v_mov_b64_e32 v[62:63], 0
	v_mov_b64_e32 v[64:65], 0
	v_mov_b64_e32 v[66:67], 0
	v_mov_b64_e32 v[68:69], 0
	v_mov_b64_e32 v[70:71], 0
	v_mov_b64_e32 v[80:81], 0
	v_mov_b64_e32 v[82:83], 0
	v_mov_b64_e32 v[84:85], 0
	v_mov_b64_e32 v[86:87], 0
	v_mov_b64_e32 v[96:97], 0
	v_mov_b64_e32 v[98:99], 0
	v_mov_b64_e32 v[100:101], 0
	v_mov_b64_e32 v[102:103], 0
	v_mov_b64_e32 v[112:113], 0
	v_mov_b64_e32 v[114:115], 0
	v_mov_b64_e32 v[116:117], 0
	v_mov_b64_e32 v[118:119], 0
	v_mov_b64_e32 v[72:73], 0
	v_mov_b64_e32 v[74:75], 0
	v_mov_b64_e32 v[76:77], 0
	v_mov_b64_e32 v[78:79], 0
	v_mov_b64_e32 v[88:89], 0
	v_mov_b64_e32 v[90:91], 0
	v_mov_b64_e32 v[92:93], 0
	v_mov_b64_e32 v[94:95], 0
	v_mov_b64_e32 v[104:105], 0
	v_mov_b64_e32 v[106:107], 0
	v_mov_b64_e32 v[108:109], 0
	v_mov_b64_e32 v[110:111], 0
	v_mov_b64_e32 v[120:121], 0
	v_mov_b64_e32 v[122:123], 0
	v_mov_b64_e32 v[124:125], 0
	v_mov_b64_e32 v[126:127], 0
